# sec 7.4 one static s_setprio 1 for waves 4-7 across the attention tile loop (ping-pong structure)
# speedup vs baseline: 1.0090x; 1.0090x over previous
; #define LAS __attribute__((address_space(3)))
; DI void u_attn2(Frame& F, int h, int qb, int sp, int ntile) {
;     ...
;     AT_LOAD(kt0)
;     for (int t = 0; t < ntile; ++t) {
;         const int kt = kt0 + t;
;         __syncthreads();
; #pragma unroll
;         for (int i = 0; i < 3; ++i) { const int p = tid + 512 * i, r = p / 24, cc = p - r * 24; *(LAS u32x4*)(Ks + r * 200 + cc * 8) = kreg[i]; }
; #pragma unroll
;         for (int i = 0; i < 2; ++i) { const int p = tid + 512 * i, r = p >> 3, cc = p & 7; *(LAS u32x4*)(Vs + r * 72 + cc * 8) = vreg[i]; }
;         __syncthreads();
;         if (t + 1 < ntile) AT_LOAD(kt + 1)
.Latt_p1:
	s_add_u32 s48, s48, 0x18000
	s_addc_u32 s49, s49, 0
	s_add_i32 m0, vcc_lo, 0xb800
	s_nop 0
	global_load_lds_dwordx4 v122, s[48:49]
	s_add_i32 m0, m0, 0x2000
	s_nop 0
	global_load_lds_dwordx4 v123, s[48:49]
	s_add_i32 m0, m0, 0x2000
	s_nop 0
	global_load_lds_dwordx4 v124, s[48:49]
	s_add_i32 m0, vcc_lo, 0x6800
	s_nop 0
	global_load_lds_dwordx4 v125, s[36:37]
	s_add_i32 m0, m0, 0x2000
	s_nop 0
	global_load_lds_dwordx4 v126, s[36:37]
	s_min_u32 vcc_hi, s24, 5
	s_lshl_b32 vcc_hi, vcc_hi, 10
	s_add_i32 vcc_hi, vcc_hi, 0xa000
	s_add_i32 vcc_hi, vcc_hi, s11
	s_add_i32 vcc_lo, vcc_lo, 0x11800
	s_cmp_lt_u32 s24, 2
	s_cselect_b32 m0, vcc_lo, vcc_hi
	s_cselect_b32 s38, s48, s36
	s_cselect_b32 s39, s49, s37
	global_load_lds_dwordx4 v127, s[38:39]
	s_add_u32 s48, s48, 0x18000
	s_addc_u32 s49, s49, 0
	s_add_u32 s36, s36, 0x80
	s_addc_u32 s37, s37, 0
	s_waitcnt vmcnt(6)
	s_mov_b32 s46, 0
	s_mov_b32 s47, 0
	s_cmp_ge_u32 s24, 4
	s_cbranch_scc0 .LBB0_2237
	s_setprio 1
	s_branch .LBB0_2237

; #define GAS __attribute__((address_space(1)))
; DI float xr16_sum(float x) { float a = x, b = x; XR_SWAP("v_permlane16_swap_b32", a, b); return a + b; }
; DI float xr32_sum(float x) { float a = x, b = x; XR_SWAP("v_permlane32_swap_b32", a, b); return a + b; }
; DI u32x2 pk4_(const f32x4 v) { u32x2 o; o.x = pk2(v.x, v.y); o.y = pk2(v.z, v.w); return o; }
; DI void u_attn2(Frame& F, int h, int qb, int sp, int ntile) {
;     ...
;                 ps = xr32_sum(xr16_sum(ps));
;     ...
;     const int slot = att_slot(h, qb, sp);
;     bf16* po = (bf16*)(ws + WS_APO) + (size_t)slot * 32768; float* pm = (float*)(ws + WS_APM) + (size_t)slot * 512;
; #pragma unroll
;     for (int db = 0; db < 8; ++db)
; #pragma unroll
;         for (int qq = 0; qq < 2; ++qq) *(GAS u32x2*)(po + (size_t)(w * 32 + qq * 16 + lc) * 128 + db * 16 + 4 * g4) = pk4_(o[db][qq]);
;     if (g4 == 0) {
; #pragma unroll
;         for (int qq = 0; qq < 2; ++qq) { *(GAS f32x2*)(pm + (w * 32 + qq * 16 + lc) * 2) = (f32x2){mrun[qq], lrun[qq]}; } }
.LBB0_2244:
	s_setprio 0
.LBB0_2245:
	s_or_b64 exec, exec, s[30:31]
	v_mov_b32_e32 v18, v165
	v_mov_b32_e32 v20, v163
	s_nop 0
	v_permlane16_swap_b32 v165, v18
	v_permlane16_swap_b32 v163, v20
	s_nop 0
	v_add_f32_e32 v165, v165, v18
	v_add_f32_e32 v163, v163, v20
	v_mov_b32_e32 v18, v165
	v_mov_b32_e32 v20, v163
	s_nop 0
	v_permlane32_swap_b32 v165, v18
	v_permlane32_swap_b32 v163, v20
	s_nop 0
	v_add_f32_e32 v165, v165, v18
	v_add_f32_e32 v163, v163, v20
	v_lshrrev_b32_e32 v2, 2, v177
	v_add_u32_e32 v4, 1, v2
	v_lshlrev_b32_e32 v2, 1, v2
	v_sub_u32_e32 v2, v177, v2
	v_mul_u32_u24_e32 v3, 0x90, v178
	v_mul_i32_i24_e32 v2, v2, v4
	v_add3_u32 v2, v176, v3, v2
	v_ashrrev_i32_e32 v3, 31, v2
	v_lshlrev_b64 v[4:5], 16, v[2:3]
	v_lshl_add_u64 v[8:9], s[22:23], 0, v[4:5]
	v_or_b32_e32 v4, s42, v161
	v_mov_b32_e32 v161, v19
	v_ashrrev_i32_e32 v5, 31, v4
	v_or_b32_e32 v14, 16, v4
	v_lshl_add_u64 v[8:9], v[8:9], 0, v[160:161]
	v_lshlrev_b64 v[12:13], 8, v[4:5]
	v_ashrrev_i32_e32 v15, 31, v14
	v_cvt_pk_bf16_f32 v10, v134, v135
	v_cvt_pk_bf16_f32 v11, v136, v137
	v_lshl_add_u64 v[12:13], v[8:9], 0, v[12:13]
	v_lshlrev_b64 v[14:15], 8, v[14:15]
	global_store_dwordx2 v[12:13], v[10:11], off
	v_cvt_pk_bf16_f32 v10, v118, v119
	v_cvt_pk_bf16_f32 v11, v120, v121
	v_lshl_add_u64 v[8:9], v[8:9], 0, v[14:15]
	global_store_dwordx2 v[8:9], v[10:11], off
	v_cvt_pk_bf16_f32 v10, v106, v107
	v_cvt_pk_bf16_f32 v11, v108, v109
	global_store_dwordx2 v[12:13], v[10:11], off offset:32
	v_cvt_pk_bf16_f32 v10, v102, v103
	v_cvt_pk_bf16_f32 v11, v104, v105
	global_store_dwordx2 v[8:9], v[10:11], off offset:32
	v_cvt_pk_bf16_f32 v10, v98, v99
	v_cvt_pk_bf16_f32 v11, v100, v101
	global_store_dwordx2 v[12:13], v[10:11], off offset:64
	v_cvt_pk_bf16_f32 v10, v94, v95
	v_cvt_pk_bf16_f32 v11, v96, v97
	global_store_dwordx2 v[8:9], v[10:11], off offset:64
	v_cvt_pk_bf16_f32 v10, v90, v91
	v_cvt_pk_bf16_f32 v11, v92, v93
	global_store_dwordx2 v[12:13], v[10:11], off offset:96
	v_cvt_pk_bf16_f32 v10, v86, v87
	v_cvt_pk_bf16_f32 v11, v88, v89
	global_store_dwordx2 v[8:9], v[10:11], off offset:96
	v_cvt_pk_bf16_f32 v10, v82, v83
	v_cvt_pk_bf16_f32 v11, v84, v85
	global_store_dwordx2 v[12:13], v[10:11], off offset:128
	v_cvt_pk_bf16_f32 v10, v78, v79
	v_cvt_pk_bf16_f32 v11, v80, v81
	global_store_dwordx2 v[8:9], v[10:11], off offset:128
	v_cvt_pk_bf16_f32 v10, v70, v71
	v_cvt_pk_bf16_f32 v11, v72, v73
	global_store_dwordx2 v[12:13], v[10:11], off offset:160
	v_cvt_pk_bf16_f32 v10, v74, v75
	v_cvt_pk_bf16_f32 v11, v76, v77
	global_store_dwordx2 v[8:9], v[10:11], off offset:160
	v_cvt_pk_bf16_f32 v10, v66, v67
	v_cvt_pk_bf16_f32 v11, v68, v69
	global_store_dwordx2 v[12:13], v[10:11], off offset:192
	v_cvt_pk_bf16_f32 v10, v58, v59
	v_cvt_pk_bf16_f32 v11, v60, v61
	v_and_b32_e32 v6, 63, v158
	global_store_dwordx2 v[8:9], v[10:11], off offset:192
	v_cvt_pk_bf16_f32 v10, v54, v55
	v_cvt_pk_bf16_f32 v11, v56, v57
	global_store_dwordx2 v[12:13], v[10:11], off offset:224
	v_cvt_pk_bf16_f32 v10, v62, v63
	v_cvt_pk_bf16_f32 v11, v64, v65
	v_cmp_gt_u32_e32 vcc, 16, v6
	global_store_dwordx2 v[8:9], v[10:11], off offset:224
	s_and_saveexec_b64 s[30:31], vcc
	v_readlane_b32 s46, v235, 30
	v_readlane_b32 s47, v235, 31
	s_cbranch_execz .LBB0_2230
	v_lshlrev_b64 v[2:3], 11, v[2:3]
	v_lshlrev_b32_e32 v4, 1, v4
	v_lshl_add_u64 v[2:3], s[26:27], 0, v[2:3]
	v_ashrrev_i32_e32 v5, 31, v4
	v_lshl_add_u64 v[2:3], v[4:5], 2, v[2:3]
	global_store_dwordx2 v[2:3], v[164:165], off
	global_store_dwordx2 v[2:3], v[162:163], off offset:128
	s_branch .LBB0_2230
